# v36 + slot positions weighted toward the ends of the attention phase (9,5,4,5,9 of 32 workgroups per XCD instead of 7,7,6,6,6)
# baseline (speedup 1.0000x reference)
.Lattn_prio_skip:
	s_add_u32 s66, s74, 0x1c600000
	s_addc_u32 s67, s75, 0
	s_add_u32 s76, s74, 0x1e600000
	s_addc_u32 s77, s75, 0
	s_add_u32 s80, s74, 0x20600000
	s_addc_u32 s81, s75, 0
	s_add_u32 s82, s74, 0x26600000
	s_addc_u32 s83, s75, 0
	s_add_u32 s84, s74, 0x2a600000
	s_addc_u32 s85, s75, 0
	s_add_u32 s6, s74, 0x180000
	s_addc_u32 s7, s75, 0
	s_ashr_i32 s0, s14, 3
	s_mul_hi_i32 s1, s0, 0x66666667
	s_lshr_b32 s2, s1, 31
	s_ashr_i32 s1, s1, 1
	v_writelane_b32 v255, s94, 20
	s_add_i32 s1, s1, s2
	s_mul_i32 s1, s1, 5
	v_writelane_b32 v255, s95, 21
	v_writelane_b32 v255, s88, 18
	s_sub_i32 s86, s0, s1
	s_cmp_eq_u32 s0, 26
	s_cselect_b32 s86, 0, s86
	s_cmp_eq_u32 s0, 22
	s_cselect_b32 s86, 0, s86
	s_cmp_eq_u32 s0, 31
	s_cselect_b32 s86, 4, s86
	s_cmp_eq_u32 s0, 27
	s_cselect_b32 s86, 4, s86
	s_cmp_eq_u32 s0, 28
	s_cselect_b32 s86, 4, s86
	s_cmpk_lt_i32 s78, 0x100
	v_writelane_b32 v255, s89, 19
	v_writelane_b32 v255, s97, 22
	s_cselect_b64 s[0:1], -1, 0
	v_writelane_b32 v255, s0, 23
	s_cmpk_gt_i32 s78, 0xff
	s_nop 0
	v_writelane_b32 v255, s1, 24
	s_cbranch_scc1 .LBB0_402
	s_cmp_gt_i32 s86, 0
	s_cselect_b64 s[0:1], -1, 0
	s_add_u32 s16, s74, 0x180010
	v_cndmask_b32_e64 v1, 0, 1, s[0:1]
	s_waitcnt vmcnt(0) lgkmcnt(0)
	v_mbcnt_lo_u32_b32 v2, -1, 0
	s_mov_b32 s11, 0
	s_addc_u32 s17, s75, 0
	v_cmp_ne_u32_e64 s[2:3], 1, v1
	v_mov_b32_e32 v3, 0
	s_mov_b64 s[18:19], 0x80
	s_mov_b64 s[20:21], 0x40000
	s_mov_b64 s[22:23], 0x80000
	s_mov_b64 s[24:25], 0xc0000
	s_mov_b64 s[26:27], 0x100000
	s_mov_b32 s87, 0x41000000
	v_mov_b32_e32 v1, 0x358637bd
	s_mov_b32 s88, 0xf800000
	v_mov_b32_e32 v223, 0x260
	s_mov_b32 s89, 0x3f4ccccd
	v_mov_b32_e32 v230, 0xff800000
	v_mbcnt_hi_u32_b32 v231, -1, v2
	s_mov_b32 s90, s78
	s_branch .LBB0_297
